# v22 + residual/norm epilogues (P4, P6): row-sum xor-16 / xor-32 exchanges through v_permlane16_swap / v_permlane32_swap instead of two dependent ds_bpermute round trips per row sum
# baseline (speedup 1.0000x reference)
.LBB0_98:
	s_bfe_i32 s2, s0, 0x80000
	s_bfe_u32 s2, s2, 0x3000c
	s_add_i32 s2, s0, s2
	s_bfe_i32 s2, s2, 0x80000
	s_sext_i32_i16 s2, s2
	s_ashr_i32 s2, s2, 3
	s_mul_hi_i32 s16, s2, 0x6000
	s_mulk_i32 s2, 0x6000
	s_add_u32 s2, s33, s2
	s_addc_u32 s41, s68, s16
	s_lshl_b32 s36, s1, 8
	s_ashr_i32 s37, s36, 31
	s_lshl_b64 s[16:17], s[36:37], 2
	v_mov_b32 v206, v0
	s_add_u32 s40, s2, s16
	v_bfe_u32 v230, v206, 6, 2
	v_bfe_u32 v231, v206, 4, 2
	s_addc_u32 s41, s41, s17
	v_lshlrev_b32_e32 v146, 7, v230
	v_mov_b32_e32 v147, v196
	v_lshl_add_u64 v[66:67], s[40:41], 0, v[146:147]
	v_lshlrev_b32_e32 v182, 4, v231
	v_mov_b32_e32 v183, v196
	s_lshl_b32 s79, s0, 8
	s_lshl_b64 s[40:41], s[36:37], 1
	v_readlane_b32 s18, v255, 47
	v_and_b32_e32 v232, 15, v206
	v_lshl_add_u64 v[176:177], v[66:67], 0, v[182:183]
	v_ashrrev_i32_e32 v66, 2, v206
	v_readlane_b32 s19, v255, 48
	s_add_u32 s40, s18, s40
	v_and_b32_e32 v233, 0xffffffc0, v66
	v_or_b32_e32 v66, s79, v232
	s_addc_u32 s41, s19, s41
	v_lshlrev_b32_e32 v184, 6, v230
	v_mov_b32_e32 v185, v196
	v_and_b32_e32 v67, 16, v206
	v_add_u32_e32 v66, v66, v233
	v_lshl_add_u64 v[68:69], s[40:41], 0, v[184:185]
	v_lshlrev_b32_e32 v186, 1, v67
	v_mov_b32_e32 v187, v196
	v_lshrrev_b32_e32 v67, 1, v206
	v_lshl_add_u64 v[68:69], v[68:69], 0, v[186:187]
	v_and_b32_e32 v188, 16, v67
	v_mov_b32_e32 v189, v196
	v_ashrrev_i32_e32 v67, 31, v66
	v_lshl_add_u64 v[68:69], v[68:69], 0, v[188:189]
	v_lshlrev_b64 v[134:135], 11, v[66:67]
	v_lshl_add_u64 v[86:87], v[68:69], 0, v[134:135]
	global_load_dwordx4 v[164:167], v[86:87], off
	v_or_b32_e32 v86, 16, v66
	v_ashrrev_i32_e32 v87, 31, v86
	v_lshlrev_b64 v[140:141], 11, v[86:87]
	v_lshl_add_u64 v[86:87], v[68:69], 0, v[140:141]
	global_load_dwordx4 v[142:145], v[86:87], off
	v_or_b32_e32 v86, 32, v66
	v_ashrrev_i32_e32 v87, 31, v86
	v_lshlrev_b64 v[168:169], 11, v[86:87]
	v_lshl_add_u64 v[86:87], v[68:69], 0, v[168:169]
	global_load_dwordx4 v[136:139], v[86:87], off
	v_or_b32_e32 v86, 48, v66
	v_ashrrev_i32_e32 v87, 31, v86
	v_lshlrev_b64 v[170:171], 11, v[86:87]
	v_lshl_add_u64 v[86:87], v[68:69], 0, v[170:171]
	global_load_dwordx4 v[130:133], v[86:87], off
	v_add_u32_e32 v202, 0x80, v66
	v_ashrrev_i32_e32 v203, 31, v202
	v_lshlrev_b64 v[172:173], 11, v[202:203]
	s_mov_b64 s[42:43], 0x48000
	v_add_u32_e32 v204, 0xb0, v66
	v_lshl_add_u64 v[86:87], v[68:69], 0, v[172:173]
	v_lshl_add_u64 v[174:175], v[134:135], 0, s[42:43]
	s_mov_b64 s[42:43], 0x50000
	v_ashrrev_i32_e32 v205, 31, v204
	global_load_dwordx4 v[110:113], v[86:87], off
	v_lshl_add_u64 v[86:87], v[68:69], 0, v[174:175]
	v_lshl_add_u64 v[190:191], v[134:135], 0, s[42:43]
	v_lshlrev_b64 v[192:193], 11, v[204:205]
	global_load_dwordx4 v[106:109], v[86:87], off
	v_lshl_add_u64 v[86:87], v[68:69], 0, v[190:191]
	v_lshl_add_u64 v[66:67], v[68:69], 0, v[192:193]
	global_load_dwordx4 v[86:89], v[86:87], off
	s_waitcnt vmcnt(0)
	v_mov_b32_e32 v194, v166
	global_load_dwordx4 v[66:69], v[66:67], off
	v_mov_b32_e32 v195, v167
	v_permlane16_swap_b32_e32 v164, v194
	v_mov_b32_e32 v243, v144
	v_mov_b32_e32 v244, v145
	v_permlane16_swap_b32_e32 v165, v195
	v_lshlrev_b32_e32 v180, 16, v164
	v_mov_b32_e32 v241, v138
	v_mov_b32_e32 v242, v139
	v_and_b32_e32 v181, 0xffff0000, v164
	v_lshlrev_b32_e32 v178, 16, v165
	v_and_b32_e32 v179, 0xffff0000, v165
	v_mov_b32_e32 v239, v132
	v_mov_b32_e32 v240, v133
	v_lshl_add_u64 v[132:133], s[40:41], 0, v[134:135]
	v_lshl_add_u64 v[132:133], v[132:133], 0, v[184:185]
	v_lshl_add_u64 v[132:133], v[132:133], 0, v[186:187]
	v_lshl_add_u64 v[134:135], v[132:133], 0, v[188:189]
	v_lshl_add_u64 v[132:133], s[40:41], 0, v[140:141]
	v_lshl_add_u64 v[132:133], v[132:133], 0, v[184:185]
	v_lshl_add_u64 v[132:133], v[132:133], 0, v[186:187]
	v_lshl_add_u64 v[138:139], v[132:133], 0, v[188:189]
	v_lshl_add_u64 v[132:133], s[40:41], 0, v[168:169]
	v_lshl_add_u64 v[132:133], v[132:133], 0, v[184:185]
	v_lshl_add_u64 v[132:133], v[132:133], 0, v[186:187]
	v_lshl_add_u64 v[140:141], v[132:133], 0, v[188:189]
	v_lshl_add_u64 v[132:133], s[40:41], 0, v[170:171]
	v_lshl_add_u64 v[132:133], v[132:133], 0, v[184:185]
	v_lshl_add_u64 v[132:133], v[132:133], 0, v[186:187]
	v_lshl_add_u64 v[168:169], v[132:133], 0, v[188:189]
	v_lshl_add_u64 v[132:133], s[40:41], 0, v[172:173]
	v_lshl_add_u64 v[132:133], v[132:133], 0, v[184:185]
	v_lshl_add_u64 v[132:133], v[132:133], 0, v[186:187]
	v_lshl_add_u64 v[170:171], v[132:133], 0, v[188:189]
	v_lshl_add_u64 v[132:133], s[40:41], 0, v[174:175]
	v_lshl_add_u64 v[132:133], v[132:133], 0, v[184:185]
	v_lshl_add_u64 v[132:133], v[132:133], 0, v[186:187]
	v_lshl_add_u64 v[172:173], v[132:133], 0, v[188:189]
	v_lshl_add_u64 v[132:133], s[40:41], 0, v[190:191]
	v_lshl_add_u64 v[132:133], v[132:133], 0, v[184:185]
	v_lshl_add_u64 v[132:133], v[132:133], 0, v[186:187]
	v_lshl_add_u64 v[174:175], v[132:133], 0, v[188:189]
	v_lshl_add_u64 v[132:133], s[40:41], 0, v[192:193]
	v_readlane_b32 s40, v254, 56
	v_readlane_b32 s41, v254, 57
	s_add_u32 s16, s40, s16
	s_addc_u32 s17, s41, s17
	v_mov_b32_e32 v237, v112
	v_mov_b32_e32 v238, v113
	v_mov_b32_e32 v235, v108
	v_mov_b32_e32 v236, v109
	v_lshl_add_u64 v[132:133], v[132:133], 0, v[184:185]
	v_lshlrev_b32_e32 v166, 16, v194
	v_and_b32_e32 v167, 0xffff0000, v194
	v_lshlrev_b32_e32 v164, 16, v195
	v_and_b32_e32 v165, 0xffff0000, v195
	v_lshl_add_u64 v[132:133], v[132:133], 0, v[186:187]
	v_lshl_add_u64 v[208:209], v[132:133], 0, v[188:189]
	v_mov_b32_e32 v207, v88
	v_mov_b32_e32 v234, v89
	v_permlane16_swap_b32_e32 v142, v243
	v_permlane16_swap_b32_e32 v143, v244
	v_permlane16_swap_b32_e32 v136, v241
	v_permlane16_swap_b32_e32 v137, v242
	v_permlane16_swap_b32_e32 v130, v239
	v_permlane16_swap_b32_e32 v131, v240
	v_permlane16_swap_b32_e32 v110, v237
	v_permlane16_swap_b32_e32 v111, v238
	v_permlane16_swap_b32_e32 v106, v235
	s_waitcnt vmcnt(0)
	v_mov_b32_e32 v197, v68
	v_mov_b32_e32 v198, v69
	v_lshl_add_u64 v[68:69], s[16:17], 0, v[146:147]
	global_load_dwordx4 v[144:147], v[176:177], off
	v_lshl_add_u64 v[132:133], v[68:69], 0, v[182:183]
	v_permlane16_swap_b32_e32 v107, v236
	v_permlane16_swap_b32_e32 v86, v207
	v_permlane16_swap_b32_e32 v87, v234
	v_permlane16_swap_b32_e32 v66, v197
	v_permlane16_swap_b32_e32 v67, v198
	v_readlane_b32 s42, v254, 58
	v_readlane_b32 s43, v254, 59
	s_waitcnt vmcnt(0)
	v_pk_fma_f32 v[108:109], v[152:153], v[144:145], v[180:181]
	v_pk_fma_f32 v[112:113], v[154:155], v[146:147], v[178:179]
	global_load_dwordx4 v[152:155], v[176:177], off offset:64
	v_pk_mul_f32 v[216:217], v[108:109], v[108:109]
	v_pk_mul_f32 v[218:219], v[112:113], v[112:113]
	s_waitcnt vmcnt(0)
	v_pk_fma_f32 v[68:69], v[160:161], v[152:153], v[166:167]
	v_pk_fma_f32 v[88:89], v[162:163], v[154:155], v[164:165]
	global_load_dwordx4 v[164:167], v[176:177], off offset:512
	global_load_dwordx4 v[160:163], v[176:177], off offset:576
	v_pk_mul_f32 v[220:221], v[68:69], v[68:69]
	v_pk_mul_f32 v[222:223], v[88:89], v[88:89]
	global_load_dwordx4 v[210:213], v[134:135], off offset:256
	global_load_dwordx4 v[192:195], v[138:139], off offset:256
	global_load_dwordx4 v[188:191], v[140:141], off offset:256
	global_load_dwordx4 v[184:187], v[168:169], off offset:256
	global_load_dwordx4 v[180:183], v[170:171], off offset:256
	global_load_dwordx4 v[176:179], v[172:173], off offset:256
	s_nop 0
	global_load_dwordx4 v[172:175], v[174:175], off offset:256
	s_nop 0
	global_load_dwordx4 v[168:171], v[208:209], off offset:256
	s_waitcnt vmcnt(7)
	v_mov_b32_e32 v141, v212
	s_nop 1
	v_permlane16_swap_b32_e32 v210, v141
	v_mov_b32_e32 v199, v213
	s_nop 1
	v_permlane16_swap_b32_e32 v211, v199
	v_lshlrev_b32_e32 v134, 16, v210
	v_and_b32_e32 v135, 0xffff0000, v210
	v_lshlrev_b32_e32 v140, 16, v141
	v_and_b32_e32 v141, 0xffff0000, v141
	v_pk_fma_f32 v[212:213], v[156:157], v[164:165], v[134:135]
	v_lshlrev_b32_e32 v134, 16, v211
	v_and_b32_e32 v135, 0xffff0000, v211
	v_pk_fma_f32 v[208:209], v[148:149], v[160:161], v[140:141]
	v_lshlrev_b32_e32 v140, 16, v199
	v_and_b32_e32 v141, 0xffff0000, v199
	v_pk_fma_f32 v[214:215], v[158:159], v[166:167], v[134:135]
	v_pk_fma_f32 v[210:211], v[150:151], v[162:163], v[140:141]
	v_add_f32_e32 v150, v220, v221
	v_add_f32_e32 v151, v222, v223
	v_pk_mul_f32 v[134:135], v[212:213], v[212:213]
	v_pk_mul_f32 v[138:139], v[214:215], v[214:215]
	v_add_f32_e32 v150, v150, v151
	v_add_f32_e32 v151, v216, v217
	v_add_f32_e32 v156, v218, v219
	v_pk_mul_f32 v[140:141], v[208:209], v[208:209]
	v_pk_mul_f32 v[148:149], v[210:211], v[210:211]
	v_add_f32_e32 v151, v151, v156
	v_add_f32_e32 v138, v138, v139
	v_add_f32_e32 v134, v134, v135
	v_add_f32_e32 v150, v151, v150
	v_add_f32_e32 v134, v134, v138
	v_add_f32_e32 v135, v148, v149
	v_add_f32_e32 v138, v140, v141
	v_add_f32_e32 v134, v150, v134
	v_add_f32_e32 v135, v138, v135
	v_add_f32_e32 v199, v135, v134
	global_load_dwordx4 v[156:159], v[132:133], off
	global_load_dwordx4 v[148:151], v[132:133], off offset:64
	global_load_dwordx4 v[138:141], v[132:133], off offset:512
	s_nop 0
	global_load_dwordx4 v[132:135], v[132:133], off offset:576
	s_waitcnt vmcnt(10)
	v_mov_b32_e32 v223, v195
	s_waitcnt vmcnt(7)
	v_mov_b32_e32 v195, v182
	s_waitcnt vmcnt(4)
	v_mov_b32_e32 v182, v171
	v_and_b32_e32 v171, 64, v224
	v_mov_b32_e32 v245, v194
	v_mov_b32_e32 v194, v183
	v_mov_b32_e32 v183, v170
	v_xor_b32_e32 v170, 16, v224
	v_add_u32_e32 v171, 64, v171
	v_cmp_lt_i32_e32 vcc, v170, v171
	v_mov_b32_e32 v216, v187
	v_mov_b32_e32 v187, v174
	v_cndmask_b32_e32 v170, v224, v170, vcc
	v_lshlrev_b32_e32 v219, 2, v170
	v_xor_b32_e32 v170, 32, v224
	v_cmp_lt_i32_e32 vcc, v170, v171
	v_and_b32_e32 v171, 0xffffff00, v206
	v_lshlrev_b32_e32 v174, 2, v232
	v_cndmask_b32_e32 v170, v224, v170, vcc
	v_lshlrev_b32_e32 v220, 2, v170
	v_lshl_add_u32 v170, v230, 10, 0
	v_add3_u32 v218, v170, v171, v174
	v_mov_b32_e32 v170, v199
	v_mov_b32_e32 v171, v199
	s_nop 1
	v_permlane16_swap_b32_e32 v170, v171
	v_mov_b32_e32 v222, v190
	v_mov_b32_e32 v221, v191
	v_mov_b32_e32 v217, v186
	v_mov_b32_e32 v191, v178
	s_waitcnt lgkmcnt(0)
	v_add_f32_e32 v170, v171, v170
	v_mov_b32_e32 v171, v170
	s_nop 1
	v_permlane32_swap_b32_e32 v170, v171
	v_mov_b32_e32 v190, v179
	v_mov_b32_e32 v186, v175
	v_permlane16_swap_b32_e32 v192, v245
	v_permlane16_swap_b32_e32 v193, v223
	v_permlane16_swap_b32_e32 v188, v222
	v_permlane16_swap_b32_e32 v189, v221
	v_permlane16_swap_b32_e32 v184, v217
	v_permlane16_swap_b32_e32 v185, v216
	v_permlane16_swap_b32_e32 v180, v195
	v_permlane16_swap_b32_e32 v181, v194
	v_permlane16_swap_b32_e32 v176, v191
	v_permlane16_swap_b32_e32 v177, v190
	v_permlane16_swap_b32_e32 v172, v187
	v_permlane16_swap_b32_e32 v173, v186
	v_permlane16_swap_b32_e32 v168, v183
	v_permlane16_swap_b32_e32 v169, v182
	v_cmp_eq_u32_e32 vcc, 0, v231
	s_and_saveexec_b64 s[16:17], vcc
	s_mov_b32 s80, 0x400001
	s_mov_b64 s[18:19], 0x1000
	s_mov_b32 s81, 0x8000
	s_mov_b32 s77, 0x7f807f81
	s_cbranch_execz .LBB0_100
	s_waitcnt lgkmcnt(0)
	v_add_f32_e32 v170, v170, v171
	ds_write_b32 v218, v170
.LBB0_100:
	s_or_b64 exec, exec, s[16:17]
	v_lshlrev_b32_e32 v170, 16, v142
	s_waitcnt lgkmcnt(0)
	v_and_b32_e32 v171, 0xffff0000, v142
	v_lshlrev_b32_e32 v142, 16, v143
	v_and_b32_e32 v143, 0xffff0000, v143
	v_lshlrev_b32_e32 v200, 16, v243
	v_and_b32_e32 v201, 0xffff0000, v243
	v_lshlrev_b32_e32 v226, 16, v244
	v_and_b32_e32 v227, 0xffff0000, v244
	v_pk_fma_f32 v[174:175], v[122:123], v[144:145], v[170:171]
	v_pk_fma_f32 v[178:179], v[124:125], v[146:147], v[142:143]
	v_pk_fma_f32 v[142:143], v[114:115], v[152:153], v[200:201]
	v_lshlrev_b32_e32 v114, 16, v192
	v_and_b32_e32 v115, 0xffff0000, v192
	v_pk_mul_f32 v[228:229], v[174:175], v[174:175]
	v_pk_mul_f32 v[246:247], v[178:179], v[178:179]
	v_pk_fma_f32 v[170:171], v[116:117], v[154:155], v[226:227]
	v_pk_fma_f32 v[122:123], v[126:127], v[164:165], v[114:115]
	v_lshlrev_b32_e32 v114, 16, v193
	v_and_b32_e32 v115, 0xffff0000, v193
	v_pk_mul_f32 v[200:201], v[142:143], v[142:143]
	v_pk_mul_f32 v[226:227], v[170:171], v[170:171]
	v_pk_fma_f32 v[124:125], v[128:129], v[166:167], v[114:115]
	v_lshlrev_b32_e32 v114, 16, v245
	v_and_b32_e32 v115, 0xffff0000, v245
	v_lshlrev_b32_e32 v116, 16, v223
	v_and_b32_e32 v117, 0xffff0000, v223
	v_add_f32_e32 v192, v246, v247
	v_add_f32_e32 v193, v228, v229
	v_pk_mul_f32 v[126:127], v[122:123], v[122:123]
	v_pk_mul_f32 v[128:129], v[124:125], v[124:125]
	v_pk_fma_f32 v[114:115], v[118:119], v[160:161], v[114:115]
	v_pk_fma_f32 v[116:117], v[120:121], v[162:163], v[116:117]
	v_add_f32_e32 v192, v193, v192
	v_add_f32_e32 v193, v226, v227
	v_add_f32_e32 v199, v200, v201
	v_pk_mul_f32 v[118:119], v[114:115], v[114:115]
	v_pk_mul_f32 v[120:121], v[116:117], v[116:117]
	v_add_f32_e32 v193, v199, v193
	v_add_f32_e32 v128, v128, v129
	v_add_f32_e32 v126, v126, v127
	v_add_f32_e32 v192, v192, v193
	v_add_f32_e32 v126, v126, v128
	v_add_f32_e32 v120, v120, v121
	v_add_f32_e32 v118, v118, v119
	v_add_f32_e32 v126, v192, v126
	v_add_f32_e32 v118, v118, v120
	v_add_f32_e32 v118, v118, v126
	v_mov_b32_e32 v119, v118
	s_nop 1
	v_permlane16_swap_b32_e32 v118, v119
	s_waitcnt lgkmcnt(0)
	v_add_f32_e32 v118, v118, v119
	v_mov_b32_e32 v119, v118
	s_nop 1
	v_permlane32_swap_b32_e32 v118, v119
	s_and_saveexec_b64 s[16:17], vcc
	s_cbranch_execz .LBB0_102
	s_waitcnt lgkmcnt(0)
	v_add_f32_e32 v118, v118, v119
	ds_write_b32 v218, v118 offset:64
.LBB0_102:
	s_or_b64 exec, exec, s[16:17]
	v_lshlrev_b32_e32 v118, 16, v136
	s_waitcnt lgkmcnt(0)
	v_and_b32_e32 v119, 0xffff0000, v136
	v_lshlrev_b32_e32 v120, 16, v137
	v_and_b32_e32 v121, 0xffff0000, v137
	v_lshlrev_b32_e32 v136, 16, v241
	v_and_b32_e32 v137, 0xffff0000, v241
	v_lshlrev_b32_e32 v192, 16, v242
	v_and_b32_e32 v193, 0xffff0000, v242
	v_pk_fma_f32 v[126:127], v[98:99], v[144:145], v[118:119]
	v_pk_fma_f32 v[128:129], v[100:101], v[146:147], v[120:121]
	v_pk_fma_f32 v[118:119], v[90:91], v[152:153], v[136:137]
	v_lshlrev_b32_e32 v90, 16, v188
	v_and_b32_e32 v91, 0xffff0000, v188
	v_pk_mul_f32 v[200:201], v[126:127], v[126:127]
	v_pk_mul_f32 v[226:227], v[128:129], v[128:129]
	v_pk_fma_f32 v[120:121], v[92:93], v[154:155], v[192:193]
	v_pk_fma_f32 v[98:99], v[102:103], v[164:165], v[90:91]
	v_lshlrev_b32_e32 v90, 16, v189
	v_and_b32_e32 v91, 0xffff0000, v189
	v_pk_mul_f32 v[136:137], v[118:119], v[118:119]
	v_pk_mul_f32 v[192:193], v[120:121], v[120:121]
	v_pk_fma_f32 v[100:101], v[104:105], v[166:167], v[90:91]
	v_lshlrev_b32_e32 v90, 16, v222
	v_and_b32_e32 v91, 0xffff0000, v222
	v_lshlrev_b32_e32 v92, 16, v221
	v_and_b32_e32 v93, 0xffff0000, v221
	v_add_f32_e32 v188, v226, v227
	v_add_f32_e32 v189, v200, v201
	v_pk_mul_f32 v[102:103], v[98:99], v[98:99]
	v_pk_mul_f32 v[104:105], v[100:101], v[100:101]
	v_pk_fma_f32 v[90:91], v[94:95], v[160:161], v[90:91]
	v_pk_fma_f32 v[92:93], v[96:97], v[162:163], v[92:93]
	v_add_f32_e32 v188, v189, v188
	v_add_f32_e32 v189, v192, v193
	v_add_f32_e32 v136, v136, v137
	v_pk_mul_f32 v[94:95], v[90:91], v[90:91]
	v_pk_mul_f32 v[96:97], v[92:93], v[92:93]
	v_add_f32_e32 v136, v136, v189
	v_add_f32_e32 v104, v104, v105
	v_add_f32_e32 v102, v102, v103
	v_add_f32_e32 v136, v188, v136
	v_add_f32_e32 v102, v102, v104
	v_add_f32_e32 v96, v96, v97
	v_add_f32_e32 v94, v94, v95
	v_add_f32_e32 v102, v136, v102
	v_add_f32_e32 v94, v94, v96
	v_add_f32_e32 v94, v94, v102
	v_mov_b32_e32 v95, v94
	s_nop 1
	v_permlane16_swap_b32_e32 v94, v95
	s_waitcnt lgkmcnt(0)
	v_add_f32_e32 v94, v94, v95
	v_mov_b32_e32 v95, v94
	s_nop 1
	v_permlane32_swap_b32_e32 v94, v95
	s_and_saveexec_b64 s[16:17], vcc
	s_cbranch_execz .LBB0_104
	s_waitcnt lgkmcnt(0)
	v_add_f32_e32 v94, v94, v95
	ds_write_b32 v218, v94 offset:128
.LBB0_104:
	s_or_b64 exec, exec, s[16:17]
	v_lshlrev_b32_e32 v94, 16, v130
	s_waitcnt lgkmcnt(0)
	v_and_b32_e32 v95, 0xffff0000, v130
	v_lshlrev_b32_e32 v96, 16, v131
	v_and_b32_e32 v97, 0xffff0000, v131
	v_lshlrev_b32_e32 v130, 16, v239
	v_and_b32_e32 v131, 0xffff0000, v239
	v_lshlrev_b32_e32 v136, 16, v240
	v_and_b32_e32 v137, 0xffff0000, v240
	v_pk_fma_f32 v[102:103], v[78:79], v[144:145], v[94:95]
	v_pk_fma_f32 v[94:95], v[70:71], v[152:153], v[130:131]
	v_lshlrev_b32_e32 v70, 16, v184
	v_and_b32_e32 v71, 0xffff0000, v184
	v_pk_fma_f32 v[104:105], v[80:81], v[146:147], v[96:97]
	v_pk_fma_f32 v[96:97], v[72:73], v[154:155], v[136:137]
	v_pk_fma_f32 v[78:79], v[82:83], v[164:165], v[70:71]
	v_lshlrev_b32_e32 v70, 16, v185
	v_and_b32_e32 v71, 0xffff0000, v185
	v_pk_mul_f32 v[188:189], v[102:103], v[102:103]
	v_pk_mul_f32 v[192:193], v[104:105], v[104:105]
	v_pk_mul_f32 v[130:131], v[94:95], v[94:95]
	v_pk_mul_f32 v[136:137], v[96:97], v[96:97]
	v_pk_fma_f32 v[80:81], v[84:85], v[166:167], v[70:71]
	v_lshlrev_b32_e32 v70, 16, v217
	v_and_b32_e32 v71, 0xffff0000, v217
	v_lshlrev_b32_e32 v72, 16, v216
	v_and_b32_e32 v73, 0xffff0000, v216
	v_pk_mul_f32 v[82:83], v[78:79], v[78:79]
	v_pk_mul_f32 v[84:85], v[80:81], v[80:81]
	v_pk_fma_f32 v[70:71], v[74:75], v[160:161], v[70:71]
	v_pk_fma_f32 v[72:73], v[76:77], v[162:163], v[72:73]
	v_add_f32_e32 v184, v192, v193
	v_add_f32_e32 v185, v188, v189
	v_add_f32_e32 v136, v136, v137
	v_add_f32_e32 v130, v130, v131
	v_pk_mul_f32 v[74:75], v[70:71], v[70:71]
	v_pk_mul_f32 v[76:77], v[72:73], v[72:73]
	v_add_f32_e32 v184, v185, v184
	v_add_f32_e32 v130, v130, v136
	v_add_f32_e32 v84, v84, v85
	v_add_f32_e32 v82, v82, v83
	v_add_f32_e32 v130, v184, v130
	v_add_f32_e32 v82, v82, v84
	v_add_f32_e32 v76, v76, v77
	v_add_f32_e32 v74, v74, v75
	v_add_f32_e32 v82, v130, v82
	v_add_f32_e32 v74, v74, v76
	v_add_f32_e32 v74, v74, v82
	v_mov_b32_e32 v75, v74
	s_nop 1
	v_permlane16_swap_b32_e32 v74, v75
	s_waitcnt lgkmcnt(0)
	v_add_f32_e32 v74, v74, v75
	v_mov_b32_e32 v75, v74
	s_nop 1
	v_permlane32_swap_b32_e32 v74, v75
	s_and_saveexec_b64 s[16:17], vcc
	s_cbranch_execz .LBB0_106
	s_waitcnt lgkmcnt(0)
	v_add_f32_e32 v74, v74, v75
	ds_write_b32 v218, v74 offset:192
.LBB0_106:
	s_or_b64 exec, exec, s[16:17]
	v_lshlrev_b32_e32 v74, 16, v110
	s_waitcnt lgkmcnt(0)
	v_and_b32_e32 v75, 0xffff0000, v110
	v_lshlrev_b32_e32 v76, 16, v111
	v_and_b32_e32 v77, 0xffff0000, v111
	v_lshlrev_b32_e32 v82, 16, v237
	v_and_b32_e32 v83, 0xffff0000, v237
	v_lshlrev_b32_e32 v84, 16, v238
	v_and_b32_e32 v85, 0xffff0000, v238
	v_pk_fma_f32 v[74:75], v[62:63], v[144:145], v[74:75]
	v_pk_fma_f32 v[76:77], v[64:65], v[146:147], v[76:77]
	v_pk_fma_f32 v[62:63], v[54:55], v[152:153], v[82:83]
	v_pk_fma_f32 v[64:65], v[56:57], v[154:155], v[84:85]
	v_lshlrev_b32_e32 v54, 16, v180
	v_and_b32_e32 v55, 0xffff0000, v180
	v_lshlrev_b32_e32 v56, 16, v181
	v_and_b32_e32 v57, 0xffff0000, v181
	v_lshlrev_b32_e32 v136, 16, v195
	v_and_b32_e32 v137, 0xffff0000, v195
	v_pk_mul_f32 v[110:111], v[74:75], v[74:75]
	v_pk_mul_f32 v[130:131], v[76:77], v[76:77]
	v_pk_mul_f32 v[82:83], v[62:63], v[62:63]
	v_pk_mul_f32 v[84:85], v[64:65], v[64:65]
	v_pk_fma_f32 v[54:55], v[58:59], v[164:165], v[54:55]
	v_pk_fma_f32 v[56:57], v[60:61], v[166:167], v[56:57]
	v_pk_fma_f32 v[50:51], v[50:51], v[160:161], v[136:137]
	v_lshlrev_b32_e32 v136, 16, v194
	v_and_b32_e32 v137, 0xffff0000, v194
	v_pk_mul_f32 v[58:59], v[54:55], v[54:55]
	v_pk_mul_f32 v[60:61], v[56:57], v[56:57]
	v_pk_fma_f32 v[52:53], v[52:53], v[162:163], v[136:137]
	v_add_f32_e32 v130, v130, v131
	v_add_f32_e32 v110, v110, v111
	v_add_f32_e32 v84, v84, v85
	v_add_f32_e32 v82, v82, v83
	v_pk_mul_f32 v[136:137], v[50:51], v[50:51]
	v_pk_mul_f32 v[180:181], v[52:53], v[52:53]
	v_add_f32_e32 v110, v110, v130
	v_add_f32_e32 v82, v82, v84
	v_add_f32_e32 v60, v60, v61
	v_add_f32_e32 v58, v58, v59
	v_add_f32_e32 v82, v110, v82
	v_add_f32_e32 v58, v58, v60
	v_add_f32_e32 v59, v180, v181
	v_add_f32_e32 v60, v136, v137
	v_add_f32_e32 v58, v82, v58
	v_add_f32_e32 v59, v60, v59
	v_add_f32_e32 v58, v59, v58
	v_mov_b32_e32 v59, v58
	s_nop 1
	v_permlane16_swap_b32_e32 v58, v59
	s_waitcnt lgkmcnt(0)
	v_add_f32_e32 v58, v58, v59
	v_mov_b32_e32 v59, v58
	s_nop 1
	v_permlane32_swap_b32_e32 v58, v59
	s_and_saveexec_b64 s[16:17], vcc
	s_cbranch_execz .LBB0_108
	s_waitcnt lgkmcnt(0)
	v_add_f32_e32 v58, v58, v59
	ds_write_b32 v218, v58 offset:512
.LBB0_108:
	s_or_b64 exec, exec, s[16:17]
	v_lshlrev_b32_e32 v58, 16, v106
	s_waitcnt lgkmcnt(0)
	v_and_b32_e32 v59, 0xffff0000, v106
	v_lshlrev_b32_e32 v60, 16, v107
	v_and_b32_e32 v61, 0xffff0000, v107
	v_lshlrev_b32_e32 v82, 16, v235
	v_and_b32_e32 v83, 0xffff0000, v235
	v_lshlrev_b32_e32 v84, 16, v236
	v_and_b32_e32 v85, 0xffff0000, v236
	v_pk_fma_f32 v[58:59], v[46:47], v[144:145], v[58:59]
	v_pk_fma_f32 v[60:61], v[48:49], v[146:147], v[60:61]
	v_pk_fma_f32 v[46:47], v[38:39], v[152:153], v[82:83]
	v_pk_fma_f32 v[48:49], v[40:41], v[154:155], v[84:85]
	v_lshlrev_b32_e32 v38, 16, v176
	v_and_b32_e32 v39, 0xffff0000, v176
	v_lshlrev_b32_e32 v40, 16, v177
	v_and_b32_e32 v41, 0xffff0000, v177
	v_lshlrev_b32_e32 v130, 16, v191
	v_and_b32_e32 v131, 0xffff0000, v191
	v_pk_mul_f32 v[106:107], v[58:59], v[58:59]
	v_pk_mul_f32 v[110:111], v[60:61], v[60:61]
	v_pk_mul_f32 v[82:83], v[46:47], v[46:47]
	v_pk_mul_f32 v[84:85], v[48:49], v[48:49]
	v_pk_fma_f32 v[38:39], v[42:43], v[164:165], v[38:39]
	v_pk_fma_f32 v[40:41], v[44:45], v[166:167], v[40:41]
	v_pk_fma_f32 v[34:35], v[34:35], v[160:161], v[130:131]
	v_lshlrev_b32_e32 v130, 16, v190
	v_and_b32_e32 v131, 0xffff0000, v190
	v_pk_mul_f32 v[42:43], v[38:39], v[38:39]
	v_pk_mul_f32 v[44:45], v[40:41], v[40:41]
	v_pk_fma_f32 v[36:37], v[36:37], v[162:163], v[130:131]
	v_add_f32_e32 v110, v110, v111
	v_add_f32_e32 v106, v106, v107
	v_add_f32_e32 v84, v84, v85
	v_add_f32_e32 v82, v82, v83
	v_pk_mul_f32 v[130:131], v[34:35], v[34:35]
	v_pk_mul_f32 v[136:137], v[36:37], v[36:37]
	v_add_f32_e32 v106, v106, v110
	v_add_f32_e32 v82, v82, v84
	v_add_f32_e32 v44, v44, v45
	v_add_f32_e32 v42, v42, v43
	v_add_f32_e32 v82, v106, v82
	v_add_f32_e32 v42, v42, v44
	v_add_f32_e32 v43, v136, v137
	v_add_f32_e32 v44, v130, v131
	v_add_f32_e32 v42, v82, v42
	v_add_f32_e32 v43, v44, v43
	v_add_f32_e32 v42, v43, v42
	v_mov_b32_e32 v43, v42
	s_nop 1
	v_permlane16_swap_b32_e32 v42, v43
	s_waitcnt lgkmcnt(0)
	v_add_f32_e32 v42, v42, v43
	v_mov_b32_e32 v43, v42
	s_nop 1
	v_permlane32_swap_b32_e32 v42, v43
	s_and_saveexec_b64 s[16:17], vcc
	s_cbranch_execz .LBB0_110
	s_waitcnt lgkmcnt(0)
	v_add_f32_e32 v42, v42, v43
	ds_write_b32 v218, v42 offset:576
.LBB0_110:
	s_or_b64 exec, exec, s[16:17]
	v_lshlrev_b32_e32 v42, 16, v86
	s_waitcnt lgkmcnt(0)
	v_and_b32_e32 v43, 0xffff0000, v86
	v_lshlrev_b32_e32 v44, 16, v87
	v_and_b32_e32 v45, 0xffff0000, v87
	v_lshlrev_b32_e32 v82, 16, v207
	v_and_b32_e32 v83, 0xffff0000, v207
	v_lshlrev_b32_e32 v84, 16, v234
	v_and_b32_e32 v85, 0xffff0000, v234
	v_pk_fma_f32 v[42:43], v[30:31], v[144:145], v[42:43]
	v_pk_fma_f32 v[44:45], v[32:33], v[146:147], v[44:45]
	v_pk_fma_f32 v[30:31], v[22:23], v[152:153], v[82:83]
	v_pk_fma_f32 v[32:33], v[24:25], v[154:155], v[84:85]
	v_lshlrev_b32_e32 v22, 16, v172
	v_and_b32_e32 v23, 0xffff0000, v172
	v_lshlrev_b32_e32 v24, 16, v173
	v_and_b32_e32 v25, 0xffff0000, v173
	v_lshlrev_b32_e32 v110, 16, v187
	v_and_b32_e32 v111, 0xffff0000, v187
	v_pk_mul_f32 v[86:87], v[42:43], v[42:43]
	v_pk_mul_f32 v[106:107], v[44:45], v[44:45]
	v_pk_mul_f32 v[82:83], v[30:31], v[30:31]
	v_pk_mul_f32 v[84:85], v[32:33], v[32:33]
	v_pk_fma_f32 v[22:23], v[26:27], v[164:165], v[22:23]
	v_pk_fma_f32 v[24:25], v[28:29], v[166:167], v[24:25]
	v_pk_fma_f32 v[18:19], v[18:19], v[160:161], v[110:111]
	v_lshlrev_b32_e32 v110, 16, v186
	v_and_b32_e32 v111, 0xffff0000, v186
	v_pk_mul_f32 v[26:27], v[22:23], v[22:23]
	v_pk_mul_f32 v[28:29], v[24:25], v[24:25]
	v_pk_fma_f32 v[20:21], v[20:21], v[162:163], v[110:111]
	v_add_f32_e32 v106, v106, v107
	v_add_f32_e32 v86, v86, v87
	v_add_f32_e32 v84, v84, v85
	v_add_f32_e32 v82, v82, v83
	v_pk_mul_f32 v[110:111], v[18:19], v[18:19]
	v_pk_mul_f32 v[130:131], v[20:21], v[20:21]
	v_add_f32_e32 v86, v86, v106
	v_add_f32_e32 v82, v82, v84
	v_add_f32_e32 v28, v28, v29
	v_add_f32_e32 v26, v26, v27
	v_add_f32_e32 v82, v86, v82
	v_add_f32_e32 v26, v26, v28
	v_add_f32_e32 v27, v130, v131
	v_add_f32_e32 v28, v110, v111
	v_add_f32_e32 v26, v82, v26
	v_add_f32_e32 v27, v28, v27
	v_add_f32_e32 v26, v27, v26
	v_mov_b32_e32 v27, v26
	s_nop 1
	v_permlane16_swap_b32_e32 v26, v27
	s_waitcnt lgkmcnt(0)
	v_add_f32_e32 v26, v26, v27
	v_mov_b32_e32 v27, v26
	s_nop 1
	v_permlane32_swap_b32_e32 v26, v27
	s_and_saveexec_b64 s[16:17], vcc
	s_cbranch_execz .LBB0_112
	s_waitcnt lgkmcnt(0)
	v_add_f32_e32 v26, v26, v27
	ds_write_b32 v218, v26 offset:640
.LBB0_112:
	s_or_b64 exec, exec, s[16:17]
	v_lshlrev_b32_e32 v26, 16, v66
	s_waitcnt lgkmcnt(0)
	v_and_b32_e32 v27, 0xffff0000, v66
	v_lshlrev_b32_e32 v28, 16, v67
	v_and_b32_e32 v29, 0xffff0000, v67
	v_lshlrev_b32_e32 v66, 16, v197
	v_and_b32_e32 v67, 0xffff0000, v197
	v_lshlrev_b32_e32 v82, 16, v198
	v_and_b32_e32 v83, 0xffff0000, v198
	v_pk_fma_f32 v[26:27], v[14:15], v[144:145], v[26:27]
	v_pk_fma_f32 v[28:29], v[16:17], v[146:147], v[28:29]
	v_pk_fma_f32 v[14:15], v[6:7], v[152:153], v[66:67]
	v_pk_fma_f32 v[16:17], v[8:9], v[154:155], v[82:83]
	v_lshlrev_b32_e32 v6, 16, v168
	v_and_b32_e32 v7, 0xffff0000, v168
	v_lshlrev_b32_e32 v8, 16, v169
	v_and_b32_e32 v9, 0xffff0000, v169
	v_lshlrev_b32_e32 v106, 16, v183
	v_and_b32_e32 v107, 0xffff0000, v183
	v_pk_mul_f32 v[84:85], v[26:27], v[26:27]
	v_pk_mul_f32 v[86:87], v[28:29], v[28:29]
	v_pk_mul_f32 v[66:67], v[14:15], v[14:15]
	v_pk_mul_f32 v[82:83], v[16:17], v[16:17]
	v_pk_fma_f32 v[6:7], v[10:11], v[164:165], v[6:7]
	v_pk_fma_f32 v[8:9], v[12:13], v[166:167], v[8:9]
	v_pk_fma_f32 v[2:3], v[2:3], v[160:161], v[106:107]
	v_lshlrev_b32_e32 v106, 16, v182
	v_and_b32_e32 v107, 0xffff0000, v182
	v_pk_mul_f32 v[10:11], v[6:7], v[6:7]
	v_pk_mul_f32 v[12:13], v[8:9], v[8:9]
	v_pk_fma_f32 v[4:5], v[4:5], v[162:163], v[106:107]
	v_add_f32_e32 v86, v86, v87
	v_add_f32_e32 v84, v84, v85
	v_add_f32_e32 v82, v82, v83
	v_add_f32_e32 v66, v66, v67
	v_pk_mul_f32 v[106:107], v[2:3], v[2:3]
	v_pk_mul_f32 v[110:111], v[4:5], v[4:5]
	v_add_f32_e32 v84, v84, v86
	v_add_f32_e32 v66, v66, v82
	v_add_f32_e32 v12, v12, v13
	v_add_f32_e32 v10, v10, v11
	v_add_f32_e32 v66, v84, v66
	v_add_f32_e32 v10, v10, v12
	v_add_f32_e32 v11, v110, v111
	v_add_f32_e32 v12, v106, v107
	v_add_f32_e32 v10, v66, v10
	v_add_f32_e32 v11, v12, v11
	v_add_f32_e32 v10, v11, v10
	v_mov_b32_e32 v11, v10
	s_nop 1
	v_permlane16_swap_b32_e32 v10, v11
	s_waitcnt lgkmcnt(0)
	v_add_f32_e32 v10, v10, v11
	v_mov_b32_e32 v11, v10
	s_nop 1
	v_permlane32_swap_b32_e32 v10, v11
	s_and_saveexec_b64 s[16:17], vcc
	s_cbranch_execz .LBB0_114
	s_waitcnt lgkmcnt(0)
	v_add_f32_e32 v10, v10, v11
	ds_write_b32 v218, v10 offset:704

.LBB0_199:
	s_bfe_i32 s1, s42, 0x80000
	s_bfe_u32 s1, s1, 0x3000c
	s_add_i32 s1, s42, s1
	s_bfe_i32 s1, s1, 0x80000
	s_sext_i32_i16 s1, s1
	s_ashr_i32 s1, s1, 3
	s_mul_hi_i32 s17, s1, 0x1800
	s_mul_i32 s16, s1, 0x1800
	s_lshl_b32 s73, s42, 8
	s_lshl_b64 s[16:17], s[16:17], 2
	s_add_u32 s36, s2, s16
	s_addc_u32 s37, s70, s17
	s_lshl_b32 s44, s0, 8
	s_ashr_i32 s45, s44, 31
	s_lshl_b64 s[0:1], s[44:45], 2
	v_mov_b32 v166, v0
	s_add_u32 s0, s36, s0
	v_bfe_u32 v167, v166, 6, 2
	v_bfe_u32 v197, v166, 4, 2
	s_addc_u32 s1, s37, s1
	v_lshlrev_b32_e32 v14, 7, v167
	v_mov_b32_e32 v15, v196
	v_lshl_add_u64 v[14:15], s[0:1], 0, v[14:15]
	v_lshlrev_b32_e32 v28, 4, v197
	v_mov_b32_e32 v29, v196
	v_lshl_add_u64 v[50:51], v[14:15], 0, v[28:29]
	v_ashrrev_i32_e32 v14, 2, v166
	v_and_b32_e32 v164, 0xffffffc0, v14
	v_and_b32_e32 v162, 15, v166
	v_lshlrev_b32_e32 v160, 5, v167
	v_lshlrev_b32_e32 v86, 2, v197
	v_add_u32_e32 v14, s73, v164
	v_or3_b32 v158, v160, s44, v86
	v_or_b32_e32 v14, v14, v162
	v_readlane_b32 s52, v254, 60
	v_ashrrev_i32_e32 v159, 31, v158
	v_readlane_b32 s53, v254, 61
	v_ashrrev_i32_e32 v15, 31, v14
	v_lshlrev_b64 v[28:29], 12, v[14:15]
	v_lshl_add_u64 v[76:77], v[158:159], 2, s[52:53]
	v_lshl_add_u64 v[28:29], v[76:77], 0, v[28:29]
	global_load_dwordx4 v[98:101], v[28:29], off
	v_or_b32_e32 v28, 16, v14
	v_ashrrev_i32_e32 v29, 31, v28
	v_lshlrev_b64 v[28:29], 12, v[28:29]
	v_lshl_add_u64 v[28:29], v[76:77], 0, v[28:29]
	global_load_dwordx4 v[88:91], v[28:29], off
	v_or_b32_e32 v28, 32, v14
	v_or_b32_e32 v14, 48, v14
	v_ashrrev_i32_e32 v29, 31, v28
	v_ashrrev_i32_e32 v15, 31, v14
	v_lshlrev_b64 v[28:29], 12, v[28:29]
	v_lshlrev_b64 v[14:15], 12, v[14:15]
	global_load_dwordx4 v[178:181], v[50:51], off
	v_lshl_add_u64 v[28:29], v[76:77], 0, v[28:29]
	v_lshl_add_u64 v[14:15], v[76:77], 0, v[14:15]
	global_load_dwordx4 v[78:81], v[28:29], off
	global_load_dwordx4 v[52:55], v[14:15], off
	v_or_b32_e32 v14, s73, v162
	v_and_b32_e32 v191, 16, v166
	v_add_u32_e32 v194, v14, v164
	v_readlane_b32 s54, v254, 62
	v_readlane_b32 s55, v254, 63
	v_readlane_b32 s56, v255, 0
	v_readlane_b32 s57, v255, 1
	v_readlane_b32 s58, v255, 2
	v_readlane_b32 s59, v255, 3
	v_readlane_b32 s60, v255, 4
	v_readlane_b32 s61, v255, 5
	v_readlane_b32 s62, v255, 6
	v_readlane_b32 s63, v255, 7
	v_readlane_b32 s64, v255, 8
	v_readlane_b32 s65, v255, 9
	v_readlane_b32 s66, v255, 10
	v_readlane_b32 s67, v255, 11
	v_and_b32_e32 v200, 8, v86
	s_waitcnt vmcnt(0)
	v_fma_f32 v163, v57, v179, v99
	v_fmac_f32_e32 v101, v59, v181
	v_fma_f32 v165, v56, v178, v98
	v_fma_f32 v161, v58, v180, v100
	v_fma_f32 v206, v10, v178, v52
	v_fma_f32 v204, v11, v179, v53
	v_mul_f32_e32 v10, v163, v163
	v_mul_f32_e32 v11, v101, v101
	v_fmac_f32_e32 v10, v165, v165
	v_fmac_f32_e32 v11, v161, v161
	v_fma_f32 v231, v38, v178, v88
	v_fma_f32 v230, v39, v179, v89
	v_fma_f32 v90, v40, v180, v90
	v_fmac_f32_e32 v91, v41, v181
	v_fma_f32 v219, v24, v178, v78
	v_fma_f32 v218, v25, v179, v79
	v_fma_f32 v217, v26, v180, v80
	v_fmac_f32_e32 v81, v27, v181
	v_fma_f32 v80, v12, v180, v54
	v_add_f32_e32 v54, v10, v11
	v_fmac_f32_e32 v55, v13, v181
	v_add_u32_e32 v198, 0x80, v194
	v_ashrrev_i32_e32 v199, 31, v198
	v_add_u32_e32 v184, 0x90, v194
	v_lshlrev_b64 v[10:11], 12, v[198:199]
	v_ashrrev_i32_e32 v185, 31, v184
	v_add_u32_e32 v182, 0xa0, v194
	v_lshl_add_u64 v[24:25], v[76:77], 0, v[10:11]
	v_lshlrev_b64 v[10:11], 12, v[184:185]
	v_ashrrev_i32_e32 v183, 31, v182
	v_add_u32_e32 v176, 0xb0, v194
	v_lshl_add_u64 v[168:169], v[76:77], 0, v[10:11]
	v_lshlrev_b64 v[10:11], 12, v[182:183]
	v_ashrrev_i32_e32 v177, 31, v176
	v_lshl_add_u64 v[170:171], v[76:77], 0, v[10:11]
	v_lshlrev_b64 v[10:11], 12, v[176:177]
	global_load_dwordx4 v[56:59], v[24:25], off
	global_load_dwordx4 v[38:41], v[168:169], off
	v_lshl_add_u64 v[172:173], v[76:77], 0, v[10:11]
	global_load_dwordx4 v[26:29], v[170:171], off
	global_load_dwordx4 v[12:15], v[172:173], off
	s_waitcnt vmcnt(3)
	v_fma_f32 v208, v154, v178, v56
	v_fma_f32 v207, v155, v179, v57
	v_fma_f32 v205, v156, v180, v58
	v_fmac_f32_e32 v59, v157, v181
	s_waitcnt vmcnt(2)
	v_fma_f32 v193, v92, v178, v38
	v_fma_f32 v192, v93, v179, v39
	v_fma_f32 v190, v94, v180, v40
	v_fmac_f32_e32 v41, v95, v181
	s_waitcnt vmcnt(1)
	v_fma_f32 v189, v82, v178, v26
	v_fma_f32 v188, v83, v179, v27
	v_fma_f32 v187, v84, v180, v28
	v_fmac_f32_e32 v29, v85, v181
	s_waitcnt vmcnt(0)
	v_fma_f32 v186, v72, v178, v12
	v_fma_f32 v28, v73, v179, v13
	v_fma_f32 v14, v74, v180, v14
	v_fmac_f32_e32 v15, v75, v181
	v_ashrrev_i32_e32 v195, 31, v194
	v_or_b32_e32 v74, 16, v194
	v_lshlrev_b64 v[10:11], 12, v[194:195]
	v_ashrrev_i32_e32 v75, 31, v74
	v_or_b32_e32 v178, 32, v194
	v_lshl_add_u64 v[26:27], v[76:77], 0, v[10:11]
	v_lshlrev_b64 v[10:11], 12, v[74:75]
	v_ashrrev_i32_e32 v179, 31, v178
	v_or_b32_e32 v180, 48, v194
	v_lshl_add_u64 v[38:39], v[76:77], 0, v[10:11]
	v_lshlrev_b64 v[10:11], 12, v[178:179]
	v_ashrrev_i32_e32 v181, 31, v180
	v_lshl_add_u64 v[52:53], v[76:77], 0, v[10:11]
	v_lshlrev_b64 v[10:11], 12, v[180:181]
	global_load_dwordx4 v[96:99], v[26:27], off offset:64
	global_load_dwordx4 v[92:95], v[38:39], off offset:64
	v_lshl_add_u64 v[174:175], v[76:77], 0, v[10:11]
	global_load_dwordx4 v[86:89], v[52:53], off offset:64
	global_load_dwordx4 v[82:85], v[174:175], off offset:64
	global_load_dwordx4 v[10:13], v[50:51], off offset:64
	s_waitcnt vmcnt(0)
	v_fma_f32 v155, v69, v11, v97
	v_fmac_f32_e32 v99, v71, v13
	v_fma_f32 v157, v68, v10, v96
	v_fma_f32 v97, v70, v12, v98
	v_mul_f32_e32 v40, v155, v155
	v_mul_f32_e32 v56, v99, v99
	v_fmac_f32_e32 v40, v157, v157
	v_fmac_f32_e32 v56, v97, v97
	v_add_f32_e32 v40, v40, v56
	v_add_f32_e32 v54, v54, v40
	v_fma_f32 v233, v60, v10, v92
	v_fma_f32 v232, v61, v11, v93
	v_fma_f32 v94, v62, v12, v94
	v_fmac_f32_e32 v95, v63, v13
	v_fma_f32 v223, v42, v10, v86
	v_fma_f32 v222, v43, v11, v87
	v_fma_f32 v88, v44, v12, v88
	v_fmac_f32_e32 v89, v45, v13
	v_fma_f32 v214, v34, v10, v82
	v_fma_f32 v213, v35, v11, v83
	v_fma_f32 v84, v36, v12, v84
	v_fmac_f32_e32 v85, v37, v13
	global_load_dwordx4 v[76:79], v[24:25], off offset:64
	global_load_dwordx4 v[70:73], v[168:169], off offset:64
	global_load_dwordx4 v[60:63], v[170:171], off offset:64
	global_load_dwordx4 v[42:45], v[172:173], off offset:64
	v_readlane_b32 s18, v255, 47
	v_lshlrev_b64 v[34:35], 11, v[194:195]
	v_readlane_b32 s19, v255, 48
	s_lshl_b64 s[0:1], s[44:45], 1
	v_lshlrev_b32_e32 v194, 6, v167
	v_lshl_add_u64 v[34:35], s[18:19], 0, v[34:35]
	v_lshl_add_u64 v[34:35], v[34:35], 0, s[0:1]
	v_mov_b32_e32 v195, v196
	v_lshl_add_u64 v[68:69], v[34:35], 0, v[194:195]
	v_lshlrev_b32_e32 v56, 1, v191
	v_mov_b32_e32 v57, v196
	v_cvt_pk_bf16_f32 v34, v165, v163
	v_cvt_pk_bf16_f32 v35, v161, v101
	v_cvt_pk_bf16_f32 v36, v157, v155
	v_cvt_pk_bf16_f32 v37, v97, v99
	v_lshl_add_u64 v[68:69], v[68:69], 0, v[56:57]
	v_lshlrev_b32_e32 v82, 1, v200
	v_mov_b32_e32 v83, v196
	v_permlane16_swap_b32_e32 v34, v36
	v_permlane16_swap_b32_e32 v35, v37
	v_lshl_add_u64 v[86:87], v[68:69], 0, v[82:83]
	global_store_dwordx4 v[86:87], v[34:37], off
	s_nop 1
	v_lshlrev_b64 v[34:35], 11, v[74:75]
	v_lshl_add_u64 v[34:35], s[18:19], 0, v[34:35]
	v_lshl_add_u64 v[34:35], v[34:35], 0, s[0:1]
	v_lshl_add_u64 v[68:69], v[34:35], 0, v[194:195]
	v_cvt_pk_bf16_f32 v34, v231, v230
	v_cvt_pk_bf16_f32 v35, v90, v91
	v_cvt_pk_bf16_f32 v36, v233, v232
	v_cvt_pk_bf16_f32 v37, v94, v95
	v_lshl_add_u64 v[68:69], v[68:69], 0, v[56:57]
	v_permlane16_swap_b32_e32 v34, v36
	v_permlane16_swap_b32_e32 v35, v37
	v_lshl_add_u64 v[92:93], v[68:69], 0, v[82:83]
	global_store_dwordx4 v[92:93], v[34:37], off
	s_nop 1
	v_lshlrev_b64 v[34:35], 11, v[178:179]
	v_lshl_add_u64 v[34:35], s[18:19], 0, v[34:35]
	v_lshl_add_u64 v[34:35], v[34:35], 0, s[0:1]
	v_lshl_add_u64 v[68:69], v[34:35], 0, v[194:195]
	v_cvt_pk_bf16_f32 v34, v219, v218
	v_cvt_pk_bf16_f32 v35, v217, v81
	v_cvt_pk_bf16_f32 v36, v223, v222
	v_cvt_pk_bf16_f32 v37, v88, v89
	v_lshl_add_u64 v[68:69], v[68:69], 0, v[56:57]
	v_permlane16_swap_b32_e32 v34, v36
	v_permlane16_swap_b32_e32 v35, v37
	v_lshl_add_u64 v[178:179], v[68:69], 0, v[82:83]
	global_store_dwordx4 v[178:179], v[34:37], off
	s_nop 1
	v_lshlrev_b64 v[34:35], 11, v[180:181]
	v_lshl_add_u64 v[34:35], s[18:19], 0, v[34:35]
	v_lshl_add_u64 v[34:35], v[34:35], 0, s[0:1]
	v_lshl_add_u64 v[68:69], v[34:35], 0, v[194:195]
	v_cvt_pk_bf16_f32 v34, v206, v204
	v_cvt_pk_bf16_f32 v35, v80, v55
	v_cvt_pk_bf16_f32 v36, v214, v213
	v_cvt_pk_bf16_f32 v37, v84, v85
	v_lshl_add_u64 v[68:69], v[68:69], 0, v[56:57]
	v_permlane16_swap_b32_e32 v34, v36
	v_permlane16_swap_b32_e32 v35, v37
	v_lshl_add_u64 v[180:181], v[68:69], 0, v[82:83]
	global_store_dwordx4 v[180:181], v[34:37], off
	s_waitcnt vmcnt(7)
	v_fma_f32 v221, v30, v10, v76
	v_fma_f32 v220, v31, v11, v77
	v_fma_f32 v78, v32, v12, v78
	v_fmac_f32_e32 v79, v33, v13
	s_waitcnt vmcnt(6)
	v_fma_f32 v216, v20, v10, v70
	v_fma_f32 v215, v21, v11, v71
	v_fma_f32 v72, v22, v12, v72
	v_fmac_f32_e32 v73, v23, v13
	s_waitcnt vmcnt(5)
	v_fma_f32 v212, v6, v10, v60
	v_fma_f32 v211, v7, v11, v61
	v_fma_f32 v62, v8, v12, v62
	v_fmac_f32_e32 v63, v9, v13
	s_waitcnt vmcnt(4)
	v_fma_f32 v210, v2, v10, v42
	v_fma_f32 v209, v3, v11, v43
	v_fma_f32 v43, v4, v12, v44
	v_fmac_f32_e32 v45, v5, v13
	global_load_dwordx4 v[32:35], v[26:27], off offset:512
	global_load_dwordx4 v[20:23], v[38:39], off offset:512
	global_load_dwordx4 v[10:13], v[52:53], off offset:512
	global_load_dwordx4 v[4:7], v[174:175], off offset:512
	global_load_dwordx4 v[68:71], v[50:51], off offset:512
	v_lshlrev_b64 v[2:3], 11, v[198:199]
	v_lshl_add_u64 v[2:3], s[18:19], 0, v[2:3]
	v_lshl_add_u64 v[2:3], v[2:3], 0, s[0:1]
	v_lshl_add_u64 v[2:3], v[2:3], 0, v[194:195]
	v_lshl_add_u64 v[2:3], v[2:3], 0, v[56:57]
	v_lshl_add_u64 v[60:61], v[2:3], 0, v[82:83]
	v_lshlrev_b64 v[2:3], 11, v[184:185]
	v_lshl_add_u64 v[2:3], s[18:19], 0, v[2:3]
	v_lshl_add_u64 v[2:3], v[2:3], 0, s[0:1]
	v_lshl_add_u64 v[2:3], v[2:3], 0, v[194:195]
	v_lshl_add_u64 v[2:3], v[2:3], 0, v[56:57]
	v_lshl_add_u64 v[184:185], v[2:3], 0, v[82:83]
	v_lshlrev_b64 v[2:3], 11, v[182:183]
	v_lshl_add_u64 v[2:3], s[18:19], 0, v[2:3]
	v_lshl_add_u64 v[2:3], v[2:3], 0, s[0:1]
	v_cvt_pk_bf16_f32 v74, v208, v207
	v_cvt_pk_bf16_f32 v75, v205, v59
	v_cvt_pk_bf16_f32 v76, v221, v220
	v_cvt_pk_bf16_f32 v77, v78, v79
	v_lshl_add_u64 v[2:3], v[2:3], 0, v[194:195]
	v_permlane16_swap_b32_e32 v74, v76
	v_permlane16_swap_b32_e32 v75, v77
	v_lshl_add_u64 v[2:3], v[2:3], 0, v[56:57]
	global_store_dwordx4 v[60:61], v[74:77], off
	v_lshl_add_u64 v[200:201], v[2:3], 0, v[82:83]
	v_lshlrev_b64 v[2:3], 11, v[176:177]
	v_cvt_pk_bf16_f32 v74, v193, v192
	v_cvt_pk_bf16_f32 v75, v190, v41
	v_cvt_pk_bf16_f32 v76, v216, v215
	v_cvt_pk_bf16_f32 v77, v72, v73
	v_lshl_add_u64 v[2:3], s[18:19], 0, v[2:3]
	v_permlane16_swap_b32_e32 v74, v76
	v_permlane16_swap_b32_e32 v75, v77
	global_store_dwordx4 v[184:185], v[74:77], off
	v_lshl_add_u64 v[2:3], v[2:3], 0, s[0:1]
	v_lshl_add_u64 v[2:3], v[2:3], 0, v[194:195]
	v_cvt_pk_bf16_f32 v74, v189, v188
	v_cvt_pk_bf16_f32 v75, v187, v29
	v_cvt_pk_bf16_f32 v76, v212, v211
	v_cvt_pk_bf16_f32 v77, v62, v63
	v_lshl_add_u64 v[2:3], v[2:3], 0, v[56:57]
	v_permlane16_swap_b32_e32 v74, v76
	v_permlane16_swap_b32_e32 v75, v77
	global_store_dwordx4 v[200:201], v[74:77], off
	v_lshl_add_u64 v[226:227], v[2:3], 0, v[82:83]
	s_nop 0
	v_cvt_pk_bf16_f32 v74, v186, v28
	v_cvt_pk_bf16_f32 v75, v14, v15
	v_cvt_pk_bf16_f32 v76, v210, v209
	v_cvt_pk_bf16_f32 v77, v43, v45
	s_nop 0
	v_permlane16_swap_b32_e32 v74, v76
	v_permlane16_swap_b32_e32 v75, v77
	global_store_dwordx4 v[226:227], v[74:77], off
	s_waitcnt vmcnt(4)
	v_fma_f32 v42, v135, v69, v33
	v_fmac_f32_e32 v35, v137, v71
	v_fma_f32 v44, v134, v68, v32
	v_fma_f32 v40, v136, v70, v34
	v_mul_f32_e32 v2, v42, v42
	v_mul_f32_e32 v3, v35, v35
	v_fmac_f32_e32 v2, v44, v44
	v_fmac_f32_e32 v3, v40, v40
	v_add_f32_e32 v2, v2, v3
	v_fma_f32 v203, v64, v68, v20
	v_fma_f32 v202, v65, v69, v21
	v_fma_f32 v198, v66, v70, v22
	v_fmac_f32_e32 v23, v67, v71
	v_fma_f32 v195, v46, v68, v10
	v_fma_f32 v194, v47, v69, v11
	v_fma_f32 v191, v48, v70, v12
	v_fmac_f32_e32 v13, v49, v71
	v_fma_f32 v183, v16, v68, v4
	v_fma_f32 v182, v17, v69, v5
	v_fma_f32 v177, v18, v70, v6
	v_fmac_f32_e32 v7, v19, v71
	v_add_f32_e32 v36, v54, v2
	global_load_dwordx4 v[30:33], v[24:25], off offset:512
	global_load_dwordx4 v[18:21], v[168:169], off offset:512
	global_load_dwordx4 v[8:11], v[170:171], off offset:512
	global_load_dwordx4 v[2:5], v[172:173], off offset:512
	s_waitcnt vmcnt(3)
	v_fma_f32 v176, v150, v68, v30
	v_fma_f32 v150, v151, v69, v31
	v_fma_f32 v137, v152, v70, v32
	v_fmac_f32_e32 v33, v153, v71
	s_waitcnt vmcnt(2)
	v_fma_f32 v136, v146, v68, v18
	v_fma_f32 v135, v147, v69, v19
	v_fma_f32 v134, v148, v70, v20
	v_fmac_f32_e32 v21, v149, v71
	s_waitcnt vmcnt(1)
	v_fma_f32 v32, v142, v68, v8
	v_fma_f32 v22, v143, v69, v9
	v_fma_f32 v20, v144, v70, v10
	v_fmac_f32_e32 v11, v145, v71
	s_waitcnt vmcnt(0)
	v_fma_f32 v12, v138, v68, v2
	v_fma_f32 v10, v139, v69, v3
	v_fma_f32 v6, v140, v70, v4
	v_fmac_f32_e32 v5, v141, v71
	global_load_dwordx4 v[74:77], v[26:27], off offset:576
	global_load_dwordx4 v[68:71], v[38:39], off offset:576
	global_load_dwordx4 v[64:67], v[52:53], off offset:576
	global_load_dwordx4 v[46:49], v[174:175], off offset:576
	global_load_dwordx4 v[138:141], v[50:51], off offset:576
	s_waitcnt vmcnt(0)
	v_fma_f32 v54, v131, v139, v75
	v_fmac_f32_e32 v77, v133, v141
	v_fma_f32 v58, v130, v138, v74
	v_fma_f32 v34, v132, v140, v76
	v_mul_f32_e32 v2, v54, v54
	v_mul_f32_e32 v3, v77, v77
	v_fmac_f32_e32 v2, v58, v58
	v_fmac_f32_e32 v3, v34, v34
	v_add_f32_e32 v2, v2, v3
	v_add_f32_e32 v8, v36, v2
	v_fma_f32 v131, v126, v138, v68
	v_fma_f32 v130, v127, v139, v69
	v_fma_f32 v127, v128, v140, v70
	v_fmac_f32_e32 v71, v129, v141
	v_fma_f32 v126, v122, v138, v64
	v_fma_f32 v123, v123, v139, v65
	v_fma_f32 v122, v124, v140, v66
	v_fmac_f32_e32 v67, v125, v141
	v_fma_f32 v118, v118, v138, v46
	v_fma_f32 v76, v119, v139, v47
	v_fma_f32 v70, v120, v140, v48
	v_fmac_f32_e32 v49, v121, v141
	global_load_dwordx4 v[50:53], v[24:25], off offset:576
	global_load_dwordx4 v[36:39], v[168:169], off offset:576
	s_nop 0
	global_load_dwordx4 v[24:27], v[170:171], off offset:576
	global_load_dwordx4 v[16:19], v[172:173], off offset:576
	v_cvt_pk_bf16_f32 v142, v44, v42
	v_cvt_pk_bf16_f32 v143, v40, v35
	v_cvt_pk_bf16_f32 v144, v58, v54
	v_cvt_pk_bf16_f32 v145, v34, v77
	s_nop 0
	v_permlane16_swap_b32_e32 v142, v144
	v_permlane16_swap_b32_e32 v143, v145
	global_store_dwordx4 v[86:87], v[142:145], off offset:256
	s_nop 1
	v_cvt_pk_bf16_f32 v142, v203, v202
	v_cvt_pk_bf16_f32 v143, v198, v23
	v_cvt_pk_bf16_f32 v144, v131, v130
	v_cvt_pk_bf16_f32 v145, v127, v71
	s_nop 0
	v_permlane16_swap_b32_e32 v142, v144
	v_permlane16_swap_b32_e32 v143, v145
	global_store_dwordx4 v[92:93], v[142:145], off offset:256
	s_nop 1
	v_cvt_pk_bf16_f32 v142, v195, v194
	v_cvt_pk_bf16_f32 v143, v191, v13
	v_cvt_pk_bf16_f32 v144, v126, v123
	v_cvt_pk_bf16_f32 v145, v122, v67
	s_nop 0
	v_permlane16_swap_b32_e32 v142, v144
	v_permlane16_swap_b32_e32 v143, v145
	global_store_dwordx4 v[178:179], v[142:145], off offset:256
	s_nop 1
	v_cvt_pk_bf16_f32 v142, v183, v182
	v_cvt_pk_bf16_f32 v143, v177, v7
	v_cvt_pk_bf16_f32 v144, v118, v76
	v_cvt_pk_bf16_f32 v145, v70, v49
	s_nop 0
	v_permlane16_swap_b32_e32 v142, v144
	v_permlane16_swap_b32_e32 v143, v145
	global_store_dwordx4 v[180:181], v[142:145], off offset:256
	s_waitcnt vmcnt(7)
	v_fma_f32 v124, v114, v138, v50
	v_fma_f32 v121, v115, v139, v51
	v_fma_f32 v120, v116, v140, v52
	v_fmac_f32_e32 v53, v117, v141
	s_waitcnt vmcnt(6)
	v_fma_f32 v119, v110, v138, v36
	v_fma_f32 v117, v111, v139, v37
	v_fma_f32 v116, v112, v140, v38
	v_fmac_f32_e32 v39, v113, v141
	s_waitcnt vmcnt(5)
	v_fma_f32 v66, v106, v138, v24
	v_fma_f32 v52, v107, v139, v25
	v_fma_f32 v48, v108, v140, v26
	v_fmac_f32_e32 v27, v109, v141
	s_waitcnt vmcnt(4)
	v_fma_f32 v38, v102, v138, v16
	v_fma_f32 v26, v103, v139, v17
	v_fma_f32 v18, v104, v140, v18
	v_fmac_f32_e32 v19, v105, v141
	v_cvt_pk_bf16_f32 v102, v176, v150
	v_cvt_pk_bf16_f32 v103, v137, v33
	v_cvt_pk_bf16_f32 v104, v124, v121
	v_cvt_pk_bf16_f32 v105, v120, v53
	s_nop 0
	v_permlane16_swap_b32_e32 v102, v104
	v_permlane16_swap_b32_e32 v103, v105
	global_store_dwordx4 v[60:61], v[102:105], off offset:256
	s_nop 1
	v_cvt_pk_bf16_f32 v102, v136, v135
	v_cvt_pk_bf16_f32 v103, v134, v21
	v_cvt_pk_bf16_f32 v104, v119, v117
	v_cvt_pk_bf16_f32 v105, v116, v39
	s_nop 0
	v_permlane16_swap_b32_e32 v102, v104
	v_permlane16_swap_b32_e32 v103, v105
	global_store_dwordx4 v[184:185], v[102:105], off offset:256
	s_nop 1
	v_cvt_pk_bf16_f32 v102, v32, v22
	v_cvt_pk_bf16_f32 v103, v20, v11
	v_cvt_pk_bf16_f32 v104, v66, v52
	v_cvt_pk_bf16_f32 v105, v48, v27
	s_nop 0
	v_permlane16_swap_b32_e32 v102, v104
	v_permlane16_swap_b32_e32 v103, v105
	global_store_dwordx4 v[200:201], v[102:105], off offset:256
	s_nop 1
	v_cvt_pk_bf16_f32 v102, v12, v10
	v_cvt_pk_bf16_f32 v103, v6, v5
	v_cvt_pk_bf16_f32 v104, v38, v26
	v_cvt_pk_bf16_f32 v105, v18, v19
	s_nop 0
	v_permlane16_swap_b32_e32 v102, v104
	v_permlane16_swap_b32_e32 v103, v105
	global_store_dwordx4 v[226:227], v[102:105], off offset:256
	v_mbcnt_hi_u32_b32 v2, -1, v252
	v_and_b32_e32 v4, 64, v2
	v_xor_b32_e32 v3, 16, v2
	v_add_u32_e32 v4, 64, v4
	v_cmp_lt_i32_e32 vcc, v3, v4
	v_xor_b32_e32 v9, 32, v2
	v_lshlrev_b32_e32 v16, 2, v162
	v_cndmask_b32_e32 v3, v2, v3, vcc
	v_cmp_lt_i32_e32 vcc, v9, v4
	v_lshlrev_b32_e32 v3, 2, v3
	s_nop 0
	v_cndmask_b32_e32 v2, v2, v9, vcc
	v_lshlrev_b32_e32 v4, 2, v2
	v_lshl_add_u32 v2, v167, 10, 0
	v_and_b32_e32 v9, 0xffffff00, v166
	v_add3_u32 v2, v2, v9, v16
	v_mov_b32_e32 v9, v8
	s_nop 1
	v_permlane16_swap_b32_e32 v8, v9
	v_cmp_eq_u32_e32 vcc, 0, v197
	s_waitcnt lgkmcnt(0)
	v_add_f32_e32 v8, v8, v9
	v_mov_b32_e32 v9, v8
	s_nop 1
	v_permlane32_swap_b32_e32 v8, v9
	s_and_saveexec_b64 s[40:41], vcc
	s_cbranch_execz .LBB0_201
	s_waitcnt lgkmcnt(0)
	v_add_f32_e32 v8, v8, v9
	ds_write_b32 v2, v8
.LBB0_201:
	s_or_b64 exec, exec, s[40:41]
	v_mul_f32_e32 v8, v230, v230
	s_waitcnt lgkmcnt(0)
	v_mul_f32_e32 v9, v91, v91
	v_fmac_f32_e32 v8, v231, v231
	v_fmac_f32_e32 v9, v90, v90
	v_add_f32_e32 v8, v8, v9
	v_mul_f32_e32 v9, v232, v232
	v_mul_f32_e32 v16, v95, v95
	v_fmac_f32_e32 v9, v233, v233
	v_fmac_f32_e32 v16, v94, v94
	v_add_f32_e32 v9, v9, v16
	v_add_f32_e32 v8, v8, v9
	v_mul_f32_e32 v9, v202, v202
	v_mul_f32_e32 v16, v23, v23
	v_fmac_f32_e32 v9, v203, v203
	v_fmac_f32_e32 v16, v198, v198
	v_add_f32_e32 v9, v9, v16
	v_add_f32_e32 v8, v8, v9
	v_mul_f32_e32 v9, v130, v130
	v_mul_f32_e32 v16, v71, v71
	v_fmac_f32_e32 v9, v131, v131
	v_fmac_f32_e32 v16, v127, v127
	v_add_f32_e32 v9, v9, v16
	v_add_f32_e32 v8, v8, v9
	v_mov_b32_e32 v9, v8
	s_nop 1
	v_permlane16_swap_b32_e32 v8, v9
	s_waitcnt lgkmcnt(0)
	v_add_f32_e32 v8, v8, v9
	v_mov_b32_e32 v9, v8
	s_nop 1
	v_permlane32_swap_b32_e32 v8, v9
	s_and_saveexec_b64 s[40:41], vcc
	s_cbranch_execz .LBB0_203
	s_waitcnt lgkmcnt(0)
	v_add_f32_e32 v8, v8, v9
	ds_write_b32 v2, v8 offset:64
.LBB0_203:
	s_or_b64 exec, exec, s[40:41]
	v_mul_f32_e32 v8, v218, v218
	s_waitcnt lgkmcnt(0)
	v_mul_f32_e32 v9, v81, v81
	v_fmac_f32_e32 v8, v219, v219
	v_fmac_f32_e32 v9, v217, v217
	v_add_f32_e32 v8, v8, v9
	v_mul_f32_e32 v9, v222, v222
	v_mul_f32_e32 v16, v89, v89
	v_fmac_f32_e32 v9, v223, v223
	v_fmac_f32_e32 v16, v88, v88
	v_add_f32_e32 v9, v9, v16
	v_add_f32_e32 v8, v8, v9
	v_mul_f32_e32 v9, v194, v194
	v_mul_f32_e32 v16, v13, v13
	v_fmac_f32_e32 v9, v195, v195
	v_fmac_f32_e32 v16, v191, v191
	v_add_f32_e32 v9, v9, v16
	v_add_f32_e32 v8, v8, v9
	v_mul_f32_e32 v9, v123, v123
	v_mul_f32_e32 v16, v67, v67
	v_fmac_f32_e32 v9, v126, v126
	v_fmac_f32_e32 v16, v122, v122
	v_add_f32_e32 v9, v9, v16
	v_add_f32_e32 v8, v8, v9
	v_mov_b32_e32 v9, v8
	s_nop 1
	v_permlane16_swap_b32_e32 v8, v9
	s_waitcnt lgkmcnt(0)
	v_add_f32_e32 v8, v8, v9
	v_mov_b32_e32 v9, v8
	s_nop 1
	v_permlane32_swap_b32_e32 v8, v9
	s_and_saveexec_b64 s[40:41], vcc
	s_cbranch_execz .LBB0_205
	s_waitcnt lgkmcnt(0)
	v_add_f32_e32 v8, v8, v9
	ds_write_b32 v2, v8 offset:128
.LBB0_205:
	s_or_b64 exec, exec, s[40:41]
	v_mul_f32_e32 v8, v204, v204
	s_waitcnt lgkmcnt(0)
	v_mul_f32_e32 v9, v55, v55
	v_fmac_f32_e32 v8, v206, v206
	v_fmac_f32_e32 v9, v80, v80
	v_add_f32_e32 v8, v8, v9
	v_mul_f32_e32 v9, v213, v213
	v_mul_f32_e32 v16, v85, v85
	v_fmac_f32_e32 v9, v214, v214
	v_fmac_f32_e32 v16, v84, v84
	v_add_f32_e32 v9, v9, v16
	v_add_f32_e32 v8, v8, v9
	v_mul_f32_e32 v9, v182, v182
	v_mul_f32_e32 v16, v7, v7
	v_fmac_f32_e32 v9, v183, v183
	v_fmac_f32_e32 v16, v177, v177
	v_add_f32_e32 v9, v9, v16
	v_add_f32_e32 v8, v8, v9
	v_mul_f32_e32 v9, v76, v76
	v_mul_f32_e32 v16, v49, v49
	v_fmac_f32_e32 v9, v118, v118
	v_fmac_f32_e32 v16, v70, v70
	v_add_f32_e32 v9, v9, v16
	v_add_f32_e32 v8, v8, v9
	v_mov_b32_e32 v9, v8
	s_nop 1
	v_permlane16_swap_b32_e32 v8, v9
	s_waitcnt lgkmcnt(0)
	v_add_f32_e32 v8, v8, v9
	v_mov_b32_e32 v9, v8
	s_nop 1
	v_permlane32_swap_b32_e32 v8, v9
	s_and_saveexec_b64 s[40:41], vcc
	s_cbranch_execz .LBB0_207
	s_waitcnt lgkmcnt(0)
	v_add_f32_e32 v8, v8, v9
	ds_write_b32 v2, v8 offset:192
.LBB0_207:
	s_or_b64 exec, exec, s[40:41]
	v_mul_f32_e32 v8, v207, v207
	s_waitcnt lgkmcnt(0)
	v_mul_f32_e32 v9, v59, v59
	v_fmac_f32_e32 v8, v208, v208
	v_fmac_f32_e32 v9, v205, v205
	v_add_f32_e32 v8, v8, v9
	v_mul_f32_e32 v9, v220, v220
	v_mul_f32_e32 v16, v79, v79
	v_fmac_f32_e32 v9, v221, v221
	v_fmac_f32_e32 v16, v78, v78
	v_add_f32_e32 v9, v9, v16
	v_add_f32_e32 v8, v8, v9
	v_mul_f32_e32 v9, v150, v150
	v_mul_f32_e32 v16, v33, v33
	v_fmac_f32_e32 v9, v176, v176
	v_fmac_f32_e32 v16, v137, v137
	v_add_f32_e32 v9, v9, v16
	v_add_f32_e32 v8, v8, v9
	v_mul_f32_e32 v9, v121, v121
	v_mul_f32_e32 v16, v53, v53
	v_fmac_f32_e32 v9, v124, v124
	v_fmac_f32_e32 v16, v120, v120
	v_add_f32_e32 v9, v9, v16
	v_add_f32_e32 v8, v8, v9
	v_mov_b32_e32 v9, v8
	s_nop 1
	v_permlane16_swap_b32_e32 v8, v9
	s_waitcnt lgkmcnt(0)
	v_add_f32_e32 v8, v8, v9
	v_mov_b32_e32 v9, v8
	s_nop 1
	v_permlane32_swap_b32_e32 v8, v9
	s_and_saveexec_b64 s[40:41], vcc
	s_cbranch_execz .LBB0_209
	s_waitcnt lgkmcnt(0)
	v_add_f32_e32 v8, v8, v9
	ds_write_b32 v2, v8 offset:512
.LBB0_209:
	s_or_b64 exec, exec, s[40:41]
	v_mul_f32_e32 v8, v192, v192
	s_waitcnt lgkmcnt(0)
	v_mul_f32_e32 v9, v41, v41
	v_fmac_f32_e32 v8, v193, v193
	v_fmac_f32_e32 v9, v190, v190
	v_add_f32_e32 v8, v8, v9
	v_mul_f32_e32 v9, v215, v215
	v_mul_f32_e32 v16, v73, v73
	v_fmac_f32_e32 v9, v216, v216
	v_fmac_f32_e32 v16, v72, v72
	v_add_f32_e32 v9, v9, v16
	v_add_f32_e32 v8, v8, v9
	v_mul_f32_e32 v9, v135, v135
	v_mul_f32_e32 v16, v21, v21
	v_fmac_f32_e32 v9, v136, v136
	v_fmac_f32_e32 v16, v134, v134
	v_add_f32_e32 v9, v9, v16
	v_add_f32_e32 v8, v8, v9
	v_mul_f32_e32 v9, v117, v117
	v_mul_f32_e32 v16, v39, v39
	v_fmac_f32_e32 v9, v119, v119
	v_fmac_f32_e32 v16, v116, v116
	v_add_f32_e32 v9, v9, v16
	v_add_f32_e32 v8, v8, v9
	v_mov_b32_e32 v9, v8
	s_nop 1
	v_permlane16_swap_b32_e32 v8, v9
	s_waitcnt lgkmcnt(0)
	v_add_f32_e32 v8, v8, v9
	v_mov_b32_e32 v9, v8
	s_nop 1
	v_permlane32_swap_b32_e32 v8, v9
	s_and_saveexec_b64 s[40:41], vcc
	s_cbranch_execz .LBB0_211
	s_waitcnt lgkmcnt(0)
	v_add_f32_e32 v8, v8, v9
	ds_write_b32 v2, v8 offset:576
.LBB0_211:
	s_or_b64 exec, exec, s[40:41]
	v_mul_f32_e32 v8, v188, v188
	s_waitcnt lgkmcnt(0)
	v_mul_f32_e32 v9, v29, v29
	v_fmac_f32_e32 v8, v189, v189
	v_fmac_f32_e32 v9, v187, v187
	v_add_f32_e32 v8, v8, v9
	v_mul_f32_e32 v9, v211, v211
	v_mul_f32_e32 v16, v63, v63
	v_fmac_f32_e32 v9, v212, v212
	v_fmac_f32_e32 v16, v62, v62
	v_add_f32_e32 v9, v9, v16
	v_add_f32_e32 v8, v8, v9
	v_mul_f32_e32 v9, v22, v22
	v_mul_f32_e32 v16, v11, v11
	v_fmac_f32_e32 v9, v32, v32
	v_fmac_f32_e32 v16, v20, v20
	v_add_f32_e32 v9, v9, v16
	v_add_f32_e32 v8, v8, v9
	v_mul_f32_e32 v9, v52, v52
	v_mul_f32_e32 v16, v27, v27
	v_fmac_f32_e32 v9, v66, v66
	v_fmac_f32_e32 v16, v48, v48
	v_add_f32_e32 v9, v9, v16
	v_add_f32_e32 v8, v8, v9
	v_mov_b32_e32 v9, v8
	s_nop 1
	v_permlane16_swap_b32_e32 v8, v9
	s_waitcnt lgkmcnt(0)
	v_add_f32_e32 v8, v8, v9
	v_mov_b32_e32 v9, v8
	s_nop 1
	v_permlane32_swap_b32_e32 v8, v9
	s_and_saveexec_b64 s[40:41], vcc
	s_cbranch_execz .LBB0_213
	s_waitcnt lgkmcnt(0)
	v_add_f32_e32 v8, v8, v9
	ds_write_b32 v2, v8 offset:640
.LBB0_213:
	s_or_b64 exec, exec, s[40:41]
	v_mul_f32_e32 v8, v28, v28
	s_waitcnt lgkmcnt(0)
	v_mul_f32_e32 v9, v15, v15
	v_fmac_f32_e32 v8, v186, v186
	v_fmac_f32_e32 v9, v14, v14
	v_add_f32_e32 v8, v8, v9
	v_mul_f32_e32 v9, v209, v209
	v_mul_f32_e32 v16, v45, v45
	v_fmac_f32_e32 v9, v210, v210
	v_fmac_f32_e32 v16, v43, v43
	v_add_f32_e32 v9, v9, v16
	v_add_f32_e32 v8, v8, v9
	v_mul_f32_e32 v9, v10, v10
	v_mul_f32_e32 v16, v5, v5
	v_fmac_f32_e32 v9, v12, v12
	v_fmac_f32_e32 v16, v6, v6
	v_add_f32_e32 v9, v9, v16
	v_add_f32_e32 v8, v8, v9
	v_mul_f32_e32 v9, v26, v26
	v_mul_f32_e32 v16, v19, v19
	v_fmac_f32_e32 v9, v38, v38
	v_fmac_f32_e32 v16, v18, v18
	v_add_f32_e32 v9, v9, v16
	v_add_f32_e32 v8, v8, v9
	v_mov_b32_e32 v3, v8
	v_mov_b32_e32 v4, v8
	s_nop 1
	v_permlane16_swap_b32_e32 v3, v4
	s_waitcnt lgkmcnt(0)
	v_add_f32_e32 v3, v4, v3
	v_mov_b32_e32 v4, v3
	s_nop 1
	v_permlane32_swap_b32_e32 v3, v4
	s_and_saveexec_b64 s[40:41], vcc
	s_cbranch_execz .LBB0_215
	s_waitcnt lgkmcnt(0)
	v_add_f32_e32 v3, v3, v4
	ds_write_b32 v2, v3 offset:704
